# rowpass wave all-reduce: DPP hops (quad_perm, row_half_mirror, row_mirror) and permlane16/32 swaps instead of six ds_bpermute round trips
# baseline (speedup 1.0000x reference)
.LBB0_30:
	s_or_b64 exec, exec, s[34:35]
	v_lshl_add_u64 v[52:53], v[48:49], 0, v[184:185]
	global_load_dwordx4 v[56:59], v[52:53], off offset:16
	global_load_dwordx4 v[60:63], v[52:53], off
	global_load_dwordx4 v[48:51], v[52:53], off offset:2064
	s_nop 0
	global_load_dwordx4 v[52:55], v[52:53], off offset:2048
	v_lshl_add_u64 v[64:65], v[64:65], 0, 1
	v_lshl_add_u64 v[68:69], v[68:69], 0, s[94:95]
	s_waitcnt vmcnt(0)
	v_mul_f32_e32 v73, v61, v61
	v_fmac_f32_e32 v73, v60, v60
	v_fmac_f32_e32 v73, v62, v62
	v_fmac_f32_e32 v73, v63, v63
	v_fmac_f32_e32 v73, v56, v56
	v_fmac_f32_e32 v73, v57, v57
	v_fmac_f32_e32 v73, v58, v58
	v_fmac_f32_e32 v73, v59, v59
	v_fmac_f32_e32 v73, v52, v52
	v_fmac_f32_e32 v73, v53, v53
	v_fmac_f32_e32 v73, v54, v54
	v_fmac_f32_e32 v73, v55, v55
	v_pk_mul_f32 v[86:87], v[48:49], v[48:49]
	s_nop 0
	v_add_f32_e32 v73, v73, v86
	v_add_f32_e32 v73, v73, v87
	v_pk_mul_f32 v[86:87], v[50:51], v[50:51]
	s_nop 0
	v_add_f32_e32 v73, v73, v86
	v_add_f32_e32 v73, v73, v87
	s_waitcnt lgkmcnt(0)
	s_nop 1
	v_add_f32_dpp v73, v73, v73 quad_perm:[1,0,3,2] row_mask:0xf bank_mask:0xf
	s_waitcnt lgkmcnt(0)
	s_nop 1
	v_add_f32_dpp v73, v73, v73 quad_perm:[2,3,0,1] row_mask:0xf bank_mask:0xf
	s_waitcnt lgkmcnt(0)
	s_nop 1
	v_add_f32_dpp v73, v73, v73 row_half_mirror row_mask:0xf bank_mask:0xf
	s_waitcnt lgkmcnt(0)
	s_nop 1
	v_add_f32_dpp v73, v73, v73 row_mirror row_mask:0xf bank_mask:0xf
	s_waitcnt lgkmcnt(0)
	v_mov_b32_e32 v75, v73
	s_nop 1
	v_permlane16_swap_b32 v75, v73
	v_add_f32_e32 v73, v73, v75
	s_waitcnt lgkmcnt(0)
	v_mov_b32_e32 v75, v73
	s_nop 1
	v_permlane32_swap_b32 v75, v73
	v_add_f32_e32 v73, v73, v75
	v_fmamk_f32 v73, v73, 0x3a800000, v219
	v_cmp_gt_f32_e32 vcc, s36, v73
	v_mul_f32_e32 v75, 0x4b800000, v73
	s_nop 0
	v_cndmask_b32_e32 v73, v73, v75, vcc
	v_rsq_f32_e32 v73, v73
	s_nop 0
	v_mul_f32_e32 v75, 0x45800000, v73
	v_cndmask_b32_e32 v73, v73, v75, vcc
	v_mul_f32_e32 v60, v60, v73
	v_mul_f32_e32 v60, v0, v60
	v_add_f32_e32 v75, 1.0, v28
	v_mul_f32_e32 v61, v61, v73
	v_fma_f32 v60, v75, v60, v16
	v_mul_f32_e32 v61, v1, v61
	v_add_f32_e32 v75, 1.0, v29
	v_mul_f32_e32 v62, v62, v73
	v_fma_f32 v61, v75, v61, v17
	v_mul_f32_e32 v62, v2, v62
	v_add_f32_e32 v75, 1.0, v30
	v_mul_f32_e32 v63, v63, v73
	v_fma_f32 v62, v75, v62, v18
	v_mul_f32_e32 v63, v3, v63
	v_add_f32_e32 v75, 1.0, v31
	v_mul_f32_e32 v56, v56, v73
	v_fma_f32 v63, v75, v63, v19
	v_mul_f32_e32 v56, v4, v56
	v_add_f32_e32 v75, 1.0, v24
	v_fma_f32 v75, v75, v56, v20
	v_mul_f32_e32 v56, v57, v73
	v_mul_f32_e32 v56, v5, v56
	v_add_f32_e32 v57, 1.0, v25
	v_fma_f32 v85, v57, v56, v21
	v_mul_f32_e32 v56, v58, v73
	v_mul_f32_e32 v56, v6, v56
	v_add_f32_e32 v57, 1.0, v26
	v_fma_f32 v86, v57, v56, v22
	v_mul_f32_e32 v56, v59, v73
	v_mul_f32_e32 v56, v7, v56
	v_add_f32_e32 v57, 1.0, v27
	v_mul_f32_e32 v52, v52, v73
	v_fma_f32 v59, v57, v56, v23
	v_cvt_pk_bf16_f32 v56, v60, v61
	v_mul_f32_e32 v52, v8, v52
	v_add_f32_e32 v60, 1.0, v44
	v_mul_f32_e32 v53, v53, v73
	v_fma_f32 v52, v60, v52, v32
	v_mul_f32_e32 v53, v9, v53
	v_add_f32_e32 v60, 1.0, v45
	v_mul_f32_e32 v54, v54, v73
	v_fma_f32 v53, v60, v53, v33
	v_mul_f32_e32 v54, v10, v54
	v_add_f32_e32 v60, 1.0, v46
	v_mul_f32_e32 v55, v55, v73
	v_fma_f32 v54, v60, v54, v34
	v_mul_f32_e32 v55, v11, v55
	v_add_f32_e32 v60, 1.0, v47
	v_mul_f32_e32 v48, v48, v73
	v_fma_f32 v55, v60, v55, v35
	v_mul_f32_e32 v48, v12, v48
	v_add_f32_e32 v60, 1.0, v40
	v_fma_f32 v60, v60, v48, v36
	v_mul_f32_e32 v48, v49, v73
	v_mul_f32_e32 v48, v13, v48
	v_add_f32_e32 v49, 1.0, v41
	v_fma_f32 v61, v49, v48, v37
	v_mul_f32_e32 v48, v50, v73
	v_mul_f32_e32 v48, v14, v48
	v_add_f32_e32 v49, 1.0, v42
	v_cvt_pk_bf16_f32 v57, v62, v63
	v_fma_f32 v62, v49, v48, v38
	v_mul_f32_e32 v48, v51, v73
	v_mul_f32_e32 v48, v15, v48
	v_add_f32_e32 v49, 1.0, v43
	v_fma_f32 v51, v49, v48, v39
	v_cvt_pk_bf16_f32 v48, v52, v53
	v_lshlrev_b64 v[52:53], 11, v[76:77]
	v_cmp_ge_i32_e32 vcc, v64, v78
	v_cvt_pk_bf16_f32 v58, v75, v85
	v_cvt_pk_bf16_f32 v59, v86, v59
	v_lshl_add_u64 v[52:53], v[66:67], 0, v[52:53]
	s_or_b64 s[30:31], vcc, s[30:31]
	v_cvt_pk_bf16_f32 v49, v54, v55
	v_cvt_pk_bf16_f32 v50, v60, v61
	v_cvt_pk_bf16_f32 v51, v62, v51
	flat_store_dwordx4 v[52:53], v[56:59]
	flat_store_dwordx4 v[52:53], v[48:51] offset:1024
	s_andn2_b64 exec, exec, s[30:31]
	s_cbranch_execz .LBB0_35

.LBB0_48:
	s_or_b64 exec, exec, s[34:35]
	v_cmp_lt_i32_e32 vcc, s33, v104
	v_mov_b64_e32 v[88:89], v[104:105]
	v_mov_b64_e32 v[90:91], v[114:115]
	s_and_saveexec_b64 s[34:35], vcc
	s_mov_b32 s4, 0x800000
	v_add_u32_e32 v88, 0xffffc000, v104
	v_mov_b32_e32 v89, v185
	v_lshlrev_b64 v[88:89], 12, v[88:89]
	v_lshl_add_u64 v[90:91], s[72:73], 0, v[88:89]
	v_mov_b32_e32 v88, v104
	v_mov_b32_e32 v89, v185
	s_or_b64 exec, exec, s[34:35]
	v_lshlrev_b64 v[124:125], 11, v[88:89]
	v_lshl_add_u64 v[96:97], v[108:109], 0, v[124:125]
	v_lshl_add_u64 v[122:123], v[90:91], 0, v[184:185]
	flat_load_dwordx4 v[90:93], v[96:97]
	s_waitcnt vmcnt(0) lgkmcnt(0)
	v_lshlrev_b32_e32 v88, 16, v90
	flat_load_dwordx4 v[96:99], v[96:97] offset:1024
	v_and_b32_e32 v89, 0xffff0000, v90
	v_lshlrev_b32_e32 v90, 16, v91
	v_and_b32_e32 v91, 0xffff0000, v91
	v_pk_mul_f32 v[148:149], v[88:89], v[88:89]
	v_pk_mul_f32 v[150:151], v[90:91], v[90:91]
	v_add_f32_e32 v119, v148, v149
	v_lshlrev_b32_e32 v94, 16, v92
	v_and_b32_e32 v95, 0xffff0000, v92
	v_add_f32_e32 v119, v119, v150
	v_pk_mul_f32 v[152:153], v[94:95], v[94:95]
	v_add_f32_e32 v119, v151, v119
	v_lshlrev_b32_e32 v92, 16, v93
	v_and_b32_e32 v93, 0xffff0000, v93
	v_add_f32_e32 v119, v152, v119
	v_pk_mul_f32 v[154:155], v[92:93], v[92:93]
	v_add_f32_e32 v119, v153, v119
	v_add_f32_e32 v119, v154, v119
	v_add_f32_e32 v119, v155, v119
	s_waitcnt vmcnt(0) lgkmcnt(0)
	v_lshlrev_b32_e32 v140, 16, v96
	v_and_b32_e32 v141, 0xffff0000, v96
	v_lshlrev_b32_e32 v142, 16, v97
	v_and_b32_e32 v143, 0xffff0000, v97
	v_lshlrev_b32_e32 v144, 16, v98
	v_and_b32_e32 v145, 0xffff0000, v98
	v_lshlrev_b32_e32 v146, 16, v99
	v_and_b32_e32 v147, 0xffff0000, v99
	global_load_dwordx4 v[96:99], v[122:123], off offset:16
	global_load_dwordx4 v[100:103], v[122:123], off
	global_load_dwordx4 v[132:135], v[122:123], off offset:2064
	global_load_dwordx4 v[136:139], v[122:123], off offset:2048
	v_pk_mul_f32 v[156:157], v[140:141], v[140:141]
	v_pk_mul_f32 v[158:159], v[142:143], v[142:143]
	v_add_f32_e32 v119, v156, v119
	v_add_f32_e32 v119, v157, v119
	v_add_f32_e32 v119, v158, v119
	v_pk_mul_f32 v[160:161], v[144:145], v[144:145]
	v_add_f32_e32 v119, v159, v119
	v_add_f32_e32 v119, v160, v119
	v_pk_mul_f32 v[162:163], v[146:147], v[146:147]
	v_add_f32_e32 v119, v161, v119
	v_add_f32_e32 v119, v162, v119
	v_add_f32_e32 v119, v163, v119
	s_waitcnt lgkmcnt(0)
	s_nop 1
	v_add_f32_dpp v119, v119, v119 quad_perm:[1,0,3,2] row_mask:0xf bank_mask:0xf
	s_waitcnt lgkmcnt(0)
	s_nop 1
	v_add_f32_dpp v119, v119, v119 quad_perm:[2,3,0,1] row_mask:0xf bank_mask:0xf
	s_waitcnt lgkmcnt(0)
	s_nop 1
	v_add_f32_dpp v119, v119, v119 row_half_mirror row_mask:0xf bank_mask:0xf
	s_waitcnt lgkmcnt(0)
	s_nop 1
	v_add_f32_dpp v119, v119, v119 row_mirror row_mask:0xf bank_mask:0xf
	s_waitcnt lgkmcnt(0)
	v_mov_b32_e32 v121, v119
	s_nop 1
	v_permlane16_swap_b32 v121, v119
	v_add_f32_e32 v119, v119, v121
	s_waitcnt lgkmcnt(0)
	v_mov_b32_e32 v121, v119
	s_nop 1
	v_permlane32_swap_b32 v121, v119
	v_add_f32_e32 v119, v119, v121
	v_fmamk_f32 v119, v119, 0x3a800000, v219
	v_cmp_gt_f32_e32 vcc, s4, v119
	v_mul_f32_e32 v121, 0x4b800000, v119
	s_nop 0
	v_cndmask_b32_e32 v119, v119, v121, vcc
	v_rsq_f32_e32 v119, v119
	s_nop 0
	v_mul_f32_e32 v121, 0x45800000, v119
	v_cndmask_b32_e32 v148, v119, v121, vcc
	v_pk_mul_f32 v[92:93], v[148:149], v[92:93] op_sel_hi:[0,1]
	v_pk_mul_f32 v[92:93], v[26:27], v[92:93]
	v_pk_mul_f32 v[88:89], v[148:149], v[88:89] op_sel_hi:[0,1]
	v_pk_mul_f32 v[88:89], v[0:1], v[88:89]
	v_pk_mul_f32 v[90:91], v[148:149], v[90:91] op_sel_hi:[0,1]
	v_pk_mul_f32 v[94:95], v[148:149], v[94:95] op_sel_hi:[0,1]
	v_pk_mul_f32 v[90:91], v[2:3], v[90:91]
	v_pk_mul_f32 v[94:95], v[24:25], v[94:95]
	v_cndmask_b32_e64 v119, 0, 1, s[28:29]
	v_cmp_ne_u32_e64 s[36:37], 1, v119
	s_andn2_b64 vcc, exec, s[28:29]
	s_waitcnt vmcnt(3)
	v_pk_fma_f32 v[98:99], v[38:39], v[92:93], v[98:99]
	v_pk_mul_f32 v[92:93], v[148:149], v[140:141] op_sel_hi:[0,1]
	v_pk_mul_f32 v[92:93], v[16:17], v[92:93]
	s_waitcnt vmcnt(2)
	v_pk_fma_f32 v[88:89], v[32:33], v[88:89], v[100:101]
	s_waitcnt vmcnt(0)
	v_pk_fma_f32 v[100:101], v[56:57], v[92:93], v[136:137]
	v_pk_mul_f32 v[92:93], v[148:149], v[142:143] op_sel_hi:[0,1]
	v_pk_mul_f32 v[92:93], v[18:19], v[92:93]
	v_pk_fma_f32 v[90:91], v[34:35], v[90:91], v[102:103]
	v_pk_fma_f32 v[96:97], v[36:37], v[94:95], v[96:97]
	v_pk_fma_f32 v[102:103], v[58:59], v[92:93], v[138:139]
	v_pk_mul_f32 v[92:93], v[148:149], v[144:145] op_sel_hi:[0,1]
	v_pk_mul_f32 v[94:95], v[148:149], v[146:147] op_sel_hi:[0,1]
	v_pk_mul_f32 v[92:93], v[20:21], v[92:93]
	v_pk_mul_f32 v[94:95], v[22:23], v[94:95]
	v_pk_fma_f32 v[92:93], v[60:61], v[92:93], v[132:133]
	v_pk_fma_f32 v[94:95], v[62:63], v[94:95], v[134:135]
	s_cbranch_vccnz .LBB0_52
	v_pk_mul_f32 v[72:73], v[88:89], v[88:89]
	v_pk_mul_f32 v[74:75], v[90:91], v[90:91]
	v_add_f32_e32 v72, v72, v73
	v_add_f32_e32 v72, v74, v72
	v_pk_mul_f32 v[84:85], v[96:97], v[96:97]
	v_add_f32_e32 v72, v75, v72
	v_add_f32_e32 v72, v84, v72
	v_pk_mul_f32 v[86:87], v[98:99], v[98:99]
	v_add_f32_e32 v72, v85, v72
	v_add_f32_e32 v72, v86, v72
	v_pk_mul_f32 v[132:133], v[100:101], v[100:101]
	v_add_f32_e32 v72, v87, v72
	v_add_f32_e32 v72, v132, v72
	v_pk_mul_f32 v[134:135], v[102:103], v[102:103]
	v_add_f32_e32 v72, v133, v72
	v_add_f32_e32 v72, v134, v72
	v_pk_mul_f32 v[136:137], v[92:93], v[92:93]
	v_add_f32_e32 v72, v135, v72
	v_add_f32_e32 v72, v136, v72
	v_pk_mul_f32 v[138:139], v[94:95], v[94:95]
	v_add_f32_e32 v72, v137, v72
	v_add_f32_e32 v72, v138, v72
	v_add_f32_e32 v72, v139, v72
	v_add_f32_e32 v74, 1.0, v52
	v_add_f32_e32 v75, 1.0, v53
	v_add_f32_e32 v84, 1.0, v55
	v_add_f32_e32 v85, 1.0, v48
	s_waitcnt lgkmcnt(0)
	s_nop 1
	v_add_f32_dpp v72, v72, v72 quad_perm:[1,0,3,2] row_mask:0xf bank_mask:0xf
	v_add_f32_e32 v134, 1.0, v78
	s_waitcnt lgkmcnt(0)
	s_nop 1
	v_add_f32_dpp v72, v72, v72 quad_perm:[2,3,0,1] row_mask:0xf bank_mask:0xf
	s_waitcnt lgkmcnt(0)
	s_nop 1
	v_add_f32_dpp v72, v72, v72 row_half_mirror row_mask:0xf bank_mask:0xf
	s_waitcnt lgkmcnt(0)
	s_nop 1
	v_add_f32_dpp v72, v72, v72 row_mirror row_mask:0xf bank_mask:0xf
	s_waitcnt lgkmcnt(0)
	v_mov_b32_e32 v73, v72
	s_nop 1
	v_permlane16_swap_b32 v73, v72
	v_add_f32_e32 v72, v72, v73
	s_waitcnt lgkmcnt(0)
	v_mov_b32_e32 v73, v72
	s_nop 1
	v_permlane32_swap_b32 v73, v72
	v_add_f32_e32 v72, v72, v73
	v_fmamk_f32 v72, v72, 0x3a800000, v219
	v_mul_f32_e32 v73, 0x4b800000, v72
	v_cmp_gt_f32_e32 vcc, s4, v72
	s_nop 1
	v_cndmask_b32_e32 v72, v72, v73, vcc
	v_rsq_f32_e32 v72, v72
	v_add_f32_e32 v73, 1.0, v54
	v_mul_f32_e32 v86, 0x45800000, v72
	v_cndmask_b32_e32 v86, v72, v86, vcc
	v_mul_f32_e32 v72, v88, v86
	v_mul_f32_e32 v87, v89, v86
	v_mul_f32_e32 v121, v91, v86
	v_mul_f32_e32 v132, v96, v86
	v_mul_f32_e32 v119, v90, v86
	v_mul_f32_e32 v133, v97, v86
	v_mul_f32_e32 v72, v4, v72
	v_mul_f32_e32 v87, v5, v87
	v_mul_f32_e32 v121, v7, v121
	v_mul_f32_e32 v132, v8, v132
	v_mul_f32_e32 v119, v6, v119
	v_mul_f32_e32 v133, v9, v133
	v_fma_f32 v72, v74, v72, v40
	v_fma_f32 v74, v75, v87, v41
	v_fma_f32 v75, v84, v121, v43
	v_fma_f32 v84, v85, v132, v44
	v_add_f32_e32 v85, 1.0, v49
	v_mul_f32_e32 v87, v98, v86
	v_fma_f32 v73, v73, v119, v42
	v_fma_f32 v85, v85, v133, v45
	v_mul_f32_e32 v87, v10, v87
	v_add_f32_e32 v119, 1.0, v50
	v_cvt_pk_bf16_f32 v72, v72, v74
	v_cvt_pk_bf16_f32 v74, v84, v85
	v_mul_f32_e32 v84, v100, v86
	v_fma_f32 v87, v119, v87, v46
	v_mul_f32_e32 v119, v99, v86
	v_mul_f32_e32 v84, v12, v84
	v_add_f32_e32 v85, 1.0, v80
	v_mul_f32_e32 v119, v11, v119
	v_add_f32_e32 v121, 1.0, v51
	v_fma_f32 v84, v85, v84, v64
	v_mul_f32_e32 v85, v101, v86
	v_fma_f32 v119, v121, v119, v47
	v_cvt_pk_bf16_f32 v73, v73, v75
	v_cvt_pk_bf16_f32 v75, v87, v119
	v_mul_f32_e32 v85, v13, v85
	v_add_f32_e32 v87, 1.0, v81
	v_fma_f32 v85, v87, v85, v65
	v_mul_f32_e32 v87, v102, v86
	v_mul_f32_e32 v87, v14, v87
	v_add_f32_e32 v119, 1.0, v82
	v_fma_f32 v87, v119, v87, v66
	v_mul_f32_e32 v119, v103, v86
	v_mul_f32_e32 v119, v15, v119
	v_add_f32_e32 v121, 1.0, v83
	v_fma_f32 v119, v121, v119, v67
	v_mul_f32_e32 v121, v92, v86
	v_mul_f32_e32 v121, v28, v121
	v_add_f32_e32 v132, 1.0, v76
	v_fma_f32 v121, v132, v121, v68
	v_mul_f32_e32 v132, v93, v86
	v_mul_f32_e32 v132, v29, v132
	v_add_f32_e32 v133, 1.0, v77
	v_fma_f32 v132, v133, v132, v69
	v_mul_f32_e32 v133, v94, v86
	v_mul_f32_e32 v133, v30, v133
	v_mul_f32_e32 v86, v95, v86
	v_fma_f32 v133, v134, v133, v70
	v_mul_f32_e32 v86, v31, v86
	v_add_f32_e32 v134, 1.0, v79
	v_fma_f32 v134, v134, v86, v71
	v_cvt_pk_bf16_f32 v84, v84, v85
	v_cvt_pk_bf16_f32 v85, v87, v119
	v_cvt_pk_bf16_f32 v86, v121, v132
	v_cvt_pk_bf16_f32 v87, v133, v134

.LBB0_75:
	s_or_b64 exec, exec, s[34:35]
	v_lshlrev_b64 v[100:101], 11, v[100:101]
	v_lshl_add_u64 v[116:117], v[84:85], 0, v[100:101]
	flat_load_dwordx4 v[112:115], v[116:117]
	s_nop 0
	flat_load_dwordx4 v[116:119], v[116:117] offset:1024
	v_lshl_add_u64 v[104:105], v[104:105], 0, v[184:185]
	global_load_dwordx4 v[120:123], v[104:105], off offset:16
	global_load_dwordx4 v[124:127], v[104:105], off
	global_load_dwordx4 v[128:131], v[104:105], off offset:2064
	global_load_dwordx4 v[132:135], v[104:105], off offset:2048
	v_lshl_add_u64 v[102:103], v[102:103], 0, v[184:185]
	v_lshl_add_u64 v[80:81], v[80:81], 0, 1
	s_mov_b64 s[94:95], 0x1000
	s_waitcnt vmcnt(0) lgkmcnt(0)
	v_lshlrev_b32_e32 v104, 16, v112
	v_and_b32_e32 v105, 0xffff0000, v112
	v_lshlrev_b32_e32 v112, 16, v113
	v_and_b32_e32 v113, 0xffff0000, v113
	v_pk_mul_f32 v[142:143], v[104:105], v[104:105]
	v_pk_mul_f32 v[144:145], v[112:113], v[112:113]
	v_add_f32_e32 v97, v142, v143
	v_lshlrev_b32_e32 v136, 16, v114
	v_and_b32_e32 v137, 0xffff0000, v114
	v_add_f32_e32 v97, v97, v144
	v_pk_mul_f32 v[146:147], v[136:137], v[136:137]
	v_add_f32_e32 v97, v145, v97
	v_lshlrev_b32_e32 v114, 16, v115
	v_and_b32_e32 v115, 0xffff0000, v115
	v_add_f32_e32 v97, v146, v97
	v_pk_mul_f32 v[148:149], v[114:115], v[114:115]
	v_add_f32_e32 v97, v147, v97
	v_lshlrev_b32_e32 v138, 16, v116
	v_and_b32_e32 v139, 0xffff0000, v116
	v_add_f32_e32 v97, v148, v97
	v_pk_mul_f32 v[150:151], v[138:139], v[138:139]
	v_add_f32_e32 v97, v149, v97
	v_lshlrev_b32_e32 v116, 16, v117
	v_and_b32_e32 v117, 0xffff0000, v117
	v_add_f32_e32 v97, v150, v97
	v_pk_mul_f32 v[152:153], v[116:117], v[116:117]
	v_add_f32_e32 v97, v151, v97
	v_lshlrev_b32_e32 v140, 16, v118
	v_and_b32_e32 v141, 0xffff0000, v118
	v_add_f32_e32 v97, v152, v97
	v_pk_mul_f32 v[154:155], v[140:141], v[140:141]
	v_add_f32_e32 v97, v153, v97
	v_lshlrev_b32_e32 v118, 16, v119
	v_and_b32_e32 v119, 0xffff0000, v119
	v_add_f32_e32 v97, v154, v97
	v_pk_mul_f32 v[156:157], v[118:119], v[118:119]
	v_add_f32_e32 v97, v155, v97
	v_add_f32_e32 v97, v156, v97
	v_add_f32_e32 v97, v157, v97
	s_waitcnt lgkmcnt(0)
	s_nop 1
	v_add_f32_dpp v97, v97, v97 quad_perm:[1,0,3,2] row_mask:0xf bank_mask:0xf
	s_waitcnt lgkmcnt(0)
	s_nop 1
	v_add_f32_dpp v97, v97, v97 quad_perm:[2,3,0,1] row_mask:0xf bank_mask:0xf
	s_waitcnt lgkmcnt(0)
	s_nop 1
	v_add_f32_dpp v97, v97, v97 row_half_mirror row_mask:0xf bank_mask:0xf
	s_waitcnt lgkmcnt(0)
	s_nop 1
	v_add_f32_dpp v97, v97, v97 row_mirror row_mask:0xf bank_mask:0xf
	s_waitcnt lgkmcnt(0)
	v_mov_b32_e32 v99, v97
	s_nop 1
	v_permlane16_swap_b32 v99, v97
	v_add_f32_e32 v97, v97, v99
	s_waitcnt lgkmcnt(0)
	v_mov_b32_e32 v99, v97
	s_nop 1
	v_permlane32_swap_b32 v99, v97
	v_add_f32_e32 v97, v97, v99
	v_fmamk_f32 v97, v97, 0x3a800000, v219
	v_mul_f32_e32 v99, 0x4b800000, v97
	v_cmp_gt_f32_e32 vcc, s4, v97
	s_nop 1
	v_cndmask_b32_e32 v97, v97, v99, vcc
	v_rsq_f32_e32 v97, v97
	s_nop 0
	v_mul_f32_e32 v99, 0x45800000, v97
	v_cndmask_b32_e32 v142, v97, v99, vcc
	v_pk_mul_f32 v[104:105], v[142:143], v[104:105] op_sel_hi:[0,1]
	v_pk_mul_f32 v[112:113], v[142:143], v[112:113] op_sel_hi:[0,1]
	v_pk_mul_f32 v[104:105], v[0:1], v[104:105]
	v_pk_mul_f32 v[136:137], v[142:143], v[136:137] op_sel_hi:[0,1]
	v_pk_mul_f32 v[114:115], v[142:143], v[114:115] op_sel_hi:[0,1]
	v_pk_mul_f32 v[138:139], v[142:143], v[138:139] op_sel_hi:[0,1]
	v_pk_mul_f32 v[116:117], v[142:143], v[116:117] op_sel_hi:[0,1]
	v_pk_mul_f32 v[140:141], v[142:143], v[140:141] op_sel_hi:[0,1]
	v_pk_mul_f32 v[118:119], v[142:143], v[118:119] op_sel_hi:[0,1]
	v_pk_mul_f32 v[142:143], v[2:3], v[112:113]
	v_pk_fma_f32 v[112:113], v[32:33], v[104:105], v[124:125]
	v_pk_mul_f32 v[144:145], v[10:11], v[114:115]
	v_pk_mul_f32 v[140:141], v[24:25], v[140:141]
	v_pk_fma_f32 v[114:115], v[34:35], v[142:143], v[126:127]
	v_pk_mul_f32 v[104:105], v[112:113], v[112:113]
	v_pk_mul_f32 v[136:137], v[8:9], v[136:137]
	v_pk_fma_f32 v[124:125], v[60:61], v[140:141], v[128:129]
	v_pk_mul_f32 v[128:129], v[114:115], v[114:115]
	v_add_f32_e32 v97, v104, v105
	v_pk_mul_f32 v[146:147], v[18:19], v[116:117]
	v_pk_mul_f32 v[148:149], v[26:27], v[118:119]
	v_pk_fma_f32 v[116:117], v[36:37], v[136:137], v[120:121]
	v_add_f32_e32 v97, v128, v97
	v_pk_fma_f32 v[126:127], v[62:63], v[148:149], v[130:131]
	v_pk_mul_f32 v[130:131], v[116:117], v[116:117]
	v_add_f32_e32 v97, v129, v97
	v_pk_mul_f32 v[138:139], v[16:17], v[138:139]
	v_pk_fma_f32 v[118:119], v[38:39], v[144:145], v[122:123]
	v_add_f32_e32 v97, v130, v97
	v_pk_fma_f32 v[120:121], v[56:57], v[138:139], v[132:133]
	v_pk_mul_f32 v[132:133], v[118:119], v[118:119]
	v_add_f32_e32 v97, v131, v97
	v_add_f32_e32 v97, v132, v97
	v_pk_fma_f32 v[122:123], v[58:59], v[146:147], v[134:135]
	v_pk_mul_f32 v[134:135], v[120:121], v[120:121]
	v_add_f32_e32 v97, v133, v97
	v_add_f32_e32 v97, v134, v97
	v_pk_mul_f32 v[136:137], v[122:123], v[122:123]
	v_add_f32_e32 v97, v135, v97
	v_add_f32_e32 v97, v136, v97
	v_pk_mul_f32 v[138:139], v[124:125], v[124:125]
	v_add_f32_e32 v97, v137, v97
	v_add_f32_e32 v97, v138, v97
	v_pk_mul_f32 v[140:141], v[126:127], v[126:127]
	v_add_f32_e32 v97, v139, v97
	v_add_f32_e32 v97, v140, v97
	v_add_f32_e32 v97, v141, v97
	v_lshl_add_u64 v[104:105], v[86:87], 0, v[100:101]
	global_store_dwordx4 v[102:103], v[112:115], off
	global_store_dwordx4 v[102:103], v[116:119], off offset:16
	global_store_dwordx4 v[102:103], v[120:123], off offset:2048
	global_store_dwordx4 v[102:103], v[124:127], off offset:2064
	v_add_f32_e32 v129, 1.0, v53
	s_waitcnt lgkmcnt(0)
	s_nop 1
	v_add_f32_dpp v97, v97, v97 quad_perm:[1,0,3,2] row_mask:0xf bank_mask:0xf
	v_add_f32_e32 v130, 1.0, v54
	v_add_f32_e32 v131, 1.0, v55
	v_add_f32_e32 v132, 1.0, v48
	v_add_f32_e32 v128, 1.0, v52
	s_waitcnt lgkmcnt(0)
	s_nop 1
	v_add_f32_dpp v97, v97, v97 quad_perm:[2,3,0,1] row_mask:0xf bank_mask:0xf
	v_add_f32_e32 v133, 1.0, v49
	v_add_f32_e32 v134, 1.0, v50
	v_add_f32_e32 v135, 1.0, v51
	v_add_f32_e32 v136, 1.0, v76
	s_waitcnt lgkmcnt(0)
	s_nop 1
	v_add_f32_dpp v97, v97, v97 row_half_mirror row_mask:0xf bank_mask:0xf
	v_add_f32_e32 v137, 1.0, v77
	v_add_f32_e32 v138, 1.0, v78
	v_add_f32_e32 v139, 1.0, v79
	v_add_f32_e32 v140, 1.0, v72
	s_waitcnt lgkmcnt(0)
	s_nop 1
	v_add_f32_dpp v97, v97, v97 row_mirror row_mask:0xf bank_mask:0xf
	v_add_f32_e32 v141, 1.0, v73
	v_add_f32_e32 v142, 1.0, v74
	v_add_f32_e32 v143, 1.0, v75
	s_waitcnt lgkmcnt(0)
	v_mov_b32_e32 v99, v97
	s_nop 1
	v_permlane16_swap_b32 v99, v97
	v_add_f32_e32 v97, v97, v99
	s_waitcnt lgkmcnt(0)
	v_mov_b32_e32 v99, v97
	s_nop 1
	v_permlane32_swap_b32 v99, v97
	v_add_f32_e32 v97, v97, v99
	v_fmamk_f32 v97, v97, 0x3a800000, v219
	v_mul_f32_e32 v99, 0x4b800000, v97
	v_cmp_gt_f32_e32 vcc, s4, v97
	s_mov_b64 s[4:5], 0x1000
	v_lshl_add_u64 v[90:91], v[90:91], 0, s[4:5]
	v_cndmask_b32_e32 v97, v97, v99, vcc
	v_rsq_f32_e32 v97, v97
	v_lshl_add_u64 v[92:93], v[92:93], 0, s[4:5]
	v_mul_f32_e32 v99, 0x45800000, v97
	v_cndmask_b32_e32 v97, v97, v99, vcc
	v_mul_f32_e32 v100, v113, v97
	v_mul_f32_e32 v101, v114, v97
	v_mul_f32_e32 v102, v115, v97
	v_mul_f32_e32 v103, v116, v97
	v_mul_f32_e32 v99, v112, v97
	v_mul_f32_e32 v112, v117, v97
	v_mul_f32_e32 v113, v118, v97
	v_mul_f32_e32 v114, v119, v97
	v_mul_f32_e32 v115, v120, v97
	v_mul_f32_e32 v100, v5, v100
	v_mul_f32_e32 v101, v6, v101
	v_mul_f32_e32 v102, v7, v102
	v_mul_f32_e32 v103, v12, v103
	v_mul_f32_e32 v116, v121, v97
	v_mul_f32_e32 v117, v122, v97
	v_mul_f32_e32 v118, v123, v97
	v_mul_f32_e32 v119, v124, v97
	v_mul_f32_e32 v120, v125, v97
	v_mul_f32_e32 v121, v126, v97
	v_mul_f32_e32 v97, v127, v97
	v_mul_f32_e32 v99, v4, v99
	v_mul_f32_e32 v112, v13, v112
	v_mul_f32_e32 v113, v14, v113
	v_mul_f32_e32 v114, v15, v114
	v_mul_f32_e32 v115, v20, v115
	v_fma_f32 v100, v129, v100, v41
	v_fma_f32 v101, v130, v101, v42
	v_fma_f32 v102, v131, v102, v43
	v_fma_f32 v103, v132, v103, v44
	v_cmp_ge_i32_e32 vcc, v80, v83
	v_mul_f32_e32 v116, v21, v116
	v_mul_f32_e32 v117, v22, v117
	v_mul_f32_e32 v118, v23, v118
	v_mul_f32_e32 v119, v28, v119
	v_mul_f32_e32 v120, v29, v120
	v_mul_f32_e32 v121, v30, v121
	v_mul_f32_e32 v97, v31, v97
	v_fma_f32 v99, v128, v99, v40
	v_fma_f32 v112, v133, v112, v45
	v_fma_f32 v113, v134, v113, v46
	v_fma_f32 v114, v135, v114, v47
	v_fma_f32 v115, v136, v115, v64
	v_cvt_pk_bf16_f32 v100, v99, v100
	v_cvt_pk_bf16_f32 v101, v101, v102
	v_cvt_pk_bf16_f32 v102, v103, v112
	v_cvt_pk_bf16_f32 v103, v113, v114
	s_or_b64 s[30:31], vcc, s[30:31]
	v_fma_f32 v116, v137, v116, v65
	v_fma_f32 v117, v138, v117, v66
	v_fma_f32 v118, v139, v118, v67
	v_fma_f32 v119, v140, v119, v68
	v_fma_f32 v120, v141, v120, v69
	v_fma_f32 v121, v142, v121, v70
	v_fma_f32 v97, v143, v97, v71
	v_cvt_pk_bf16_f32 v112, v115, v116
	v_cvt_pk_bf16_f32 v113, v117, v118
	v_cvt_pk_bf16_f32 v114, v119, v120
	v_cvt_pk_bf16_f32 v115, v121, v97
	flat_store_dwordx4 v[104:105], v[100:103]
	flat_store_dwordx4 v[104:105], v[112:115] offset:1024
	s_andn2_b64 exec, exec, s[30:31]
	s_cbranch_execz .LBB0_80
